# attention: V-fragment LDS reads of two PV MFMA groups issued up front with counted lgkmcnt (were read-wait-MFMA chains)
# baseline (speedup 1.0000x reference)
.LBB0_331:
	ds_read_b128 v[192:195], v175 offset:17472
	ds_read_b128 v[196:199], v175 offset:19776
	ds_read_b128 v[200:203], v175 offset:22080
	ds_read_b128 v[204:207], v175 offset:24384
	ds_read_b128 v[224:227], v175 offset:26688
	ds_read_b128 v[228:231], v175 offset:28992
	ds_read_b128 v[232:235], v175 offset:31296
	ds_read_b128 v[236:239], v175 offset:33600
	v_sub_f32_e32 v103, v103, v99
	v_mul_f32_e32 v103, 0x3fb8aa3b, v103
	v_sub_f32_e32 v102, v102, v99
	v_exp_f32_e32 v103, v103
	v_mul_f32_e32 v102, 0x3fb8aa3b, v102
	v_sub_f32_e32 v101, v101, v99
	v_exp_f32_e32 v102, v102
	v_mul_f32_e32 v101, 0x3fb8aa3b, v101
	v_sub_f32_e32 v98, v98, v99
	v_exp_f32_e32 v101, v101
	v_mul_f32_e32 v98, 0x3fb8aa3b, v98
	v_sub_f32_e32 v107, v107, v99
	v_add_f32_e32 v108, 0, v180
	v_exp_f32_e32 v110, v98
	v_mul_f32_e32 v107, 0x3fb8aa3b, v107
	v_sub_f32_e32 v106, v106, v99
	v_add_f32_e32 v108, v181, v108
	v_add_f32_e32 v109, 0, v103
	v_exp_f32_e32 v107, v107
	v_mul_f32_e32 v106, 0x3fb8aa3b, v106
	v_sub_f32_e32 v105, v105, v99
	v_add_f32_e32 v108, v182, v108
	v_add_f32_e32 v109, v102, v109
	v_exp_f32_e32 v106, v106
	v_mul_f32_e32 v105, 0x3fb8aa3b, v105
	v_sub_f32_e32 v104, v104, v99
	v_add_f32_e32 v108, v183, v108
	v_add_f32_e32 v109, v101, v109
	v_exp_f32_e32 v105, v105
	v_mul_f32_e32 v104, 0x3fb8aa3b, v104
	v_add_f32_e32 v108, v184, v108
	v_add_f32_e32 v98, v110, v109
	v_exp_f32_e32 v104, v104
	v_add_f32_e32 v108, v185, v108
	v_add_f32_e32 v98, v107, v98
	v_add_f32_e32 v108, v186, v108
	v_add_f32_e32 v98, v106, v98
	v_add_f32_e32 v108, v187, v108
	v_add_f32_e32 v98, v105, v98
	v_fmac_f32_e32 v108, v173, v138
	v_add_f32_e32 v98, v104, v98
	v_fmac_f32_e32 v98, v108, v100
	v_cvt_pk_bf16_f32 v100, v103, v102
	v_cvt_pk_bf16_f32 v101, v101, v110
	v_cvt_pk_bf16_f32 v102, v107, v106
	v_cvt_pk_bf16_f32 v103, v105, v104
	s_waitcnt lgkmcnt(7)
	v_mfma_f32_16x16x32_bf16 v[94:97], v[192:195], v[100:103], v[94:97]
	s_waitcnt lgkmcnt(6)
	v_mfma_f32_16x16x32_bf16 v[86:89], v[196:199], v[100:103], v[86:89]
	s_waitcnt lgkmcnt(5)
	v_mfma_f32_16x16x32_bf16 v[90:93], v[200:203], v[100:103], v[90:93]
	s_waitcnt lgkmcnt(4)
	v_mfma_f32_16x16x32_bf16 v[82:85], v[204:207], v[100:103], v[82:85]
	s_waitcnt lgkmcnt(3)
	v_mfma_f32_16x16x32_bf16 v[78:81], v[224:227], v[100:103], v[78:81]
	s_waitcnt lgkmcnt(2)
	v_mfma_f32_16x16x32_bf16 v[74:77], v[228:231], v[100:103], v[74:77]
	s_waitcnt lgkmcnt(1)
	v_mfma_f32_16x16x32_bf16 v[70:73], v[232:235], v[100:103], v[70:73]
	s_waitcnt lgkmcnt(0)
	v_mfma_f32_16x16x32_bf16 v[66:69], v[236:239], v[100:103], v[66:69]

.LBB0_353:
	v_sub_f32_e32 v68, v71, v67
	v_mul_f32_e32 v68, 0x3fb8aa3b, v68
	v_sub_f32_e32 v70, v70, v67
	v_exp_f32_e32 v68, v68
	v_mul_f32_e32 v70, 0x3fb8aa3b, v70
	v_sub_f32_e32 v71, v73, v67
	v_exp_f32_e32 v70, v70
	v_mul_f32_e32 v71, 0x3fb8aa3b, v71
	v_sub_f32_e32 v72, v72, v67
	v_exp_f32_e32 v71, v71
	v_mul_f32_e32 v72, 0x3fb8aa3b, v72
	v_sub_f32_e32 v73, v75, v67
	v_exp_f32_e32 v72, v72
	v_mul_f32_e32 v73, 0x3fb8aa3b, v73
	v_sub_f32_e32 v74, v74, v67
	v_add_f32_e32 v69, 0, v68
	v_exp_f32_e32 v73, v73
	v_mul_f32_e32 v74, 0x3fb8aa3b, v74
	v_sub_f32_e32 v75, v77, v67
	v_add_f32_e32 v69, v70, v69
	v_exp_f32_e32 v74, v74
	v_mul_f32_e32 v75, 0x3fb8aa3b, v75
	v_sub_f32_e32 v76, v76, v67
	v_add_f32_e32 v69, v71, v69
	v_exp_f32_e32 v75, v75
	v_mul_f32_e32 v76, 0x3fb8aa3b, v76
	v_add_f32_e32 v69, v72, v69
	v_exp_f32_e32 v76, v76
	v_add_f32_e32 v69, v73, v69
	v_add_f32_e32 v69, v74, v69
	v_add_f32_e32 v69, v75, v69
	v_add_f32_e32 v77, v76, v69
	v_fmac_f32_e32 v77, v173, v66
	v_lshl_add_u32 v66, v131, 1, s86
	v_add3_u32 v66, v66, v150, v117
	ds_read_b128 v[192:195], v66 offset:17408
	ds_read_b128 v[196:199], v66 offset:19712
	ds_read_b128 v[200:203], v66 offset:22016
	ds_read_b128 v[204:207], v66 offset:24320
	ds_read_b128 v[224:227], v66 offset:26624
	ds_read_b128 v[228:231], v66 offset:28928
	ds_read_b128 v[232:235], v66 offset:31232
	ds_read_b128 v[236:239], v66 offset:33536
	v_cvt_pk_bf16_f32 v68, v68, v70
	v_cvt_pk_bf16_f32 v69, v71, v72
	v_cvt_pk_bf16_f32 v70, v73, v74
	v_cvt_pk_bf16_f32 v71, v75, v76
	s_waitcnt lgkmcnt(7)
	v_mfma_f32_16x16x32_bf16 v[62:65], v[192:195], v[68:71], v[62:65]
	v_mov_b32_e32 v174, v67
	v_mov_b32_e32 v173, v77
	s_waitcnt lgkmcnt(6)
	v_mfma_f32_16x16x32_bf16 v[58:61], v[196:199], v[68:71], v[58:61]
	s_waitcnt lgkmcnt(5)
	v_mfma_f32_16x16x32_bf16 v[54:57], v[200:203], v[68:71], v[54:57]
	s_waitcnt lgkmcnt(4)
	v_mfma_f32_16x16x32_bf16 v[50:53], v[204:207], v[68:71], v[50:53]
	s_waitcnt lgkmcnt(3)
	v_mfma_f32_16x16x32_bf16 v[46:49], v[224:227], v[68:71], v[46:49]
	s_waitcnt lgkmcnt(2)
	v_mfma_f32_16x16x32_bf16 v[42:45], v[228:231], v[68:71], v[42:45]
	s_waitcnt lgkmcnt(1)
	v_mfma_f32_16x16x32_bf16 v[38:41], v[232:235], v[68:71], v[38:41]
	s_waitcnt lgkmcnt(0)
	v_mfma_f32_16x16x32_bf16 v[34:37], v[236:239], v[68:71], v[34:37]
